# attention phase start desynchronised: workgroups 128..255 (no sample-diff unit; the dynamic stick-breaking queue rebalances their work) with bit 3 set start two sleeps late
# baseline (speedup 1.0000x reference)
; #define LAS __attribute__((address_space(3)))
; __device__ __forceinline__ void attention_phase(const Args& A, LAS unsigned char* lds, int wave, int lane) {
;     unsigned char* ws = A.ws;
;     const bf16 *Qd = (const bf16*)(ws + WS_QD), *Qs = (const bf16*)(ws + WS_QS), *Kd = (const bf16*)(ws + WS_KD), *Ks = (const bf16*)(ws + WS_KS), *VdT = (const bf16*)(ws + WS_VDT), *VsT = (const bf16*)(ws + WS_VST);
;     bf16* MIX = (bf16*)(ws + WS_MIX);
;     const int h = lane >> 5, r = lane & 31, kap = kappa(r);
;     const int G = gridDim.x;
;     float lam;
;     { const float a = wave_sum(A.in[9][lane] * A.in[10][lane]), b = wave_sum(A.in[11][lane] * A.in[12][lane]); lam = expf(a) - expf(b) + 0.2f; }
;     const float* ghead = A.in[13];
;     const int slot = wave & 3, comp = wave >> 2;
;     for (int it = blockIdx.x; it < 256; it += G) {
.LBB0_447:
	s_or_b64 exec, exec, s[0:1]
	v_readlane_b32 s52, v250, 26
	s_waitcnt lgkmcnt(0)
	v_lshlrev_b32_e32 v0, 2, v136
	v_readlane_b32 s54, v250, 28
	v_readlane_b32 s55, v250, 29
	s_barrier
	s_cmp_lt_u32 s22, 128
	s_cbranch_scc1 .Lstag_p2
	s_bitcmp1_b32 s22, 3
	s_cbranch_scc0 .Lstag_p2
	s_sleep 127
	s_sleep 127
.Lstag_p2:
	v_readlane_b32 s56, v250, 30
	v_readlane_b32 s57, v250, 31
	v_readlane_b32 s58, v250, 32
	v_readlane_b32 s59, v250, 33
	v_readlane_b32 s60, v250, 34
	v_readlane_b32 s61, v250, 35
	global_load_dword v1, v0, s[54:55]
	global_load_dword v2, v0, s[56:57]
	s_nop 0
	global_load_dword v3, v0, s[58:59]
	s_nop 0
	global_load_dword v0, v0, s[60:61]
	v_mbcnt_hi_u32_b32 v4, -1, v137
	v_and_b32_e32 v6, 64, v4
	v_xor_b32_e32 v7, 1, v4
	v_add_u32_e32 v6, 64, v6
	v_cmp_lt_i32_e32 vcc, v7, v6
	v_xor_b32_e32 v8, 2, v4
	v_xor_b32_e32 v9, 4, v4
	v_cndmask_b32_e32 v7, v4, v7, vcc
	v_lshlrev_b32_e32 v196, 2, v7
	v_cmp_lt_i32_e32 vcc, v8, v6
	v_xor_b32_e32 v10, 8, v4
	v_xor_b32_e32 v11, 16, v4
	v_cndmask_b32_e32 v8, v4, v8, vcc
	v_lshlrev_b32_e32 v197, 2, v8
	v_cmp_lt_i32_e32 vcc, v9, v6
	v_xor_b32_e32 v12, 32, v4
	s_add_u32 s4, s80, 0xcc00000
	s_addc_u32 s5, s81, 0
	v_readlane_b32 s53, v250, 27
	v_readlane_b32 s62, v250, 36
	v_readlane_b32 s63, v250, 37
	v_readlane_b32 s64, v250, 38
	v_readlane_b32 s65, v250, 39
	v_readlane_b32 s66, v250, 40
	v_readlane_b32 s67, v250, 41
	v_writelane_b32 v250, s4, 47
	s_mov_b32 s0, 0x3fb8aa3b
	s_mov_b32 s2, 0xc2ce8ed0
	v_writelane_b32 v250, s5, 48
	s_mov_b32 s3, 0x42b17218
	v_readlane_b32 s1, v250, 9
	s_bfe_u32 s18, s1, 0x20006
	s_lshr_b32 s19, s1, 8
	s_cmpk_lt_i32 s22, 0x100
	s_cselect_b64 s[4:5], -1, 0
	v_writelane_b32 v250, s4, 51
	s_cmpk_gt_i32 s22, 0xff
	v_mov_b32_e32 v5, 0x7f800000
	v_writelane_b32 v250, s5, 52
	s_mov_b64 s[68:69], s[40:41]
	s_mov_b32 s21, 0
	v_lshrrev_b32_e32 v137, 3, v138
	s_waitcnt vmcnt(2)
	v_mul_f32_e32 v7, v1, v2
	ds_bpermute_b32 v7, v196, v7
	s_waitcnt vmcnt(0)
	v_mul_f32_e32 v13, v3, v0
	ds_bpermute_b32 v13, v196, v13
	s_waitcnt lgkmcnt(1)
	v_fmac_f32_e32 v7, v1, v2
	v_cndmask_b32_e32 v2, v4, v9, vcc
	s_waitcnt lgkmcnt(0)
	v_fmac_f32_e32 v13, v3, v0
	ds_bpermute_b32 v0, v197, v7
	ds_bpermute_b32 v1, v197, v13
	v_lshlrev_b32_e32 v198, 2, v2
	v_cmp_lt_i32_e32 vcc, v10, v6
	s_waitcnt lgkmcnt(1)
	v_add_f32_e32 v0, v7, v0
	s_waitcnt lgkmcnt(0)
	v_add_f32_e32 v1, v13, v1
	ds_bpermute_b32 v2, v198, v0
	ds_bpermute_b32 v3, v198, v1
	v_cndmask_b32_e32 v7, v4, v10, vcc
	v_lshlrev_b32_e32 v199, 2, v7
	v_cmp_lt_i32_e32 vcc, v11, v6
	s_waitcnt lgkmcnt(1)
	v_add_f32_e32 v0, v0, v2
	s_waitcnt lgkmcnt(0)
	v_add_f32_e32 v1, v1, v3
	ds_bpermute_b32 v2, v199, v0
	ds_bpermute_b32 v3, v199, v1
	v_cndmask_b32_e32 v7, v4, v11, vcc
	v_lshlrev_b32_e32 v200, 2, v7
	v_cmp_lt_i32_e32 vcc, v12, v6
	s_waitcnt lgkmcnt(1)
	v_add_f32_e32 v0, v0, v2
	s_waitcnt lgkmcnt(0)
	v_add_f32_e32 v1, v1, v3
	ds_bpermute_b32 v2, v200, v0
	ds_bpermute_b32 v3, v200, v1
	v_cndmask_b32_e32 v4, v4, v12, vcc
	v_lshlrev_b32_e32 v201, 2, v4
	s_waitcnt lgkmcnt(1)
	v_add_f32_e32 v0, v0, v2
	s_waitcnt lgkmcnt(0)
	v_add_f32_e32 v1, v1, v3
	ds_bpermute_b32 v2, v201, v0
	ds_bpermute_b32 v3, v201, v1
	s_waitcnt lgkmcnt(1)
	v_add_f32_e32 v0, v0, v2
	s_waitcnt lgkmcnt(0)
	v_add_f32_e32 v1, v1, v3
	v_mul_f32_e32 v2, 0x3fb8aa3b, v0
	v_mul_f32_e32 v3, 0x3fb8aa3b, v1
	v_fma_f32 v4, v0, s0, -v2
	v_rndne_f32_e32 v6, v2
	v_fma_f32 v7, v1, s0, -v3
	v_rndne_f32_e32 v8, v3
	v_fmac_f32_e32 v4, 0x32a5705f, v0
	v_sub_f32_e32 v2, v2, v6
	v_fmac_f32_e32 v7, 0x32a5705f, v1
	v_sub_f32_e32 v3, v3, v8
	v_add_f32_e32 v2, v2, v4
	v_cvt_i32_f32_e32 v6, v6
	v_add_f32_e32 v3, v3, v7
	v_exp_f32_e32 v2, v2
	v_cvt_i32_f32_e32 v8, v8
	v_exp_f32_e32 v3, v3
	s_cselect_b64 s[0:1], -1, 0
	v_writelane_b32 v250, s0, 49
	s_and_b64 vcc, exec, s[0:1]
	v_ldexp_f32 v2, v2, v6
	v_writelane_b32 v250, s1, 50
	v_cmp_ngt_f32_e64 s[0:1], s2, v0
	v_ldexp_f32 v3, v3, v8
	s_nop 0
	v_cndmask_b32_e64 v2, 0, v2, s[0:1]
	v_cmp_ngt_f32_e64 s[0:1], s2, v1
	s_nop 1
	v_cndmask_b32_e64 v3, 0, v3, s[0:1]
	v_cmp_nlt_f32_e64 s[0:1], s3, v0
	s_nop 1
	v_cndmask_b32_e64 v0, v5, v2, s[0:1]
	v_cmp_nlt_f32_e64 s[0:1], s3, v1
	s_nop 1
	v_cndmask_b32_e64 v1, v5, v3, s[0:1]
	v_sub_f32_e32 v0, v0, v1
	v_add_f32_e32 v202, 0x3e4ccccd, v0
	s_cbranch_vccnz .LBB0_500
; #define LAS __attribute__((address_space(3)))
; __device__ __forceinline__ void diff_unit_lds(LAS unsigned char* lds, const bf16* Qd, const bf16* Kd, const bf16* VdT, bf16* MIX, const float* ghead, float lam, int head, int u, int wave, int lane) {
;     const int h = lane >> 5, r = lane & 31, kap = kappa(r), slot = wave & 3, comp = wave >> 2;
;     const int row = 128 * u + 32 * slot + r;
;     const int nT = 2 * u + 3, Tlast = 2 * u + 1 + (slot >> 1);
;     const bf16* qrow = Qd + (size_t)row * 512 + head * 128 + comp * 64;
;     bf16x8 qf[4];
; #pragma unroll
;     for (int ds = 0; ds < 4; ++ds) qf[ds] = *(const bf16x8*)(qrow + 16 * ds + 8 * h);
;     const int koff = comp * 8192 + kap * 128, kx = (kap >> 1) & 7;
;     const int voff = 16384 + r * 128, vx = (r >> 1) & 7;
;     const int srow = 8 * wave + (lane >> 3), sc = (lane & 7) ^ ((srow >> 1) & 7);
;     const bf16* gk = Kd + (size_t)srow * 512 + head * 128 + sc * 8;
;     const bf16* gv = VdT + (size_t)(head * 128 + srow) * VPITCH + sc * 8;
;     const unsigned lbase = (unsigned)(size_t)lds + (unsigned)wave * 1024u;
;     ...
;     f32x16 O[4]; float m_used = 0.f, l = 0.f;
;     f32x16 NEGM;
; #pragma unroll
;     for (int i = 0; i < 16; ++i) NEGM[i] = 0.f;
; #pragma unroll
;     for (int b = 0; b < 4; ++b)
; #pragma unroll
;         for (int i = 0; i < 16; ++i) O[b][i] = 0.f;
;     asm volatile("" : "+v"(qf[0]), "+v"(qf[1]), "+v"(qf[2]), "+v"(qf[3]));
	v_lshrrev_b32_e32 v8, 1, v136
	v_and_b32_e32 v0, 3, v138
	s_lshr_b32 s23, s18, 1
	s_lshl_b32 s0, s19, 7
	v_lshrrev_b32_e32 v1, 5, v136
	v_and_or_b32 v9, v8, 12, v0
	s_add_u32 s0, s14, s0
	v_mov_b32_e32 v0, 0
	v_lshlrev_b32_e32 v4, 2, v138
	s_addc_u32 s1, s15, 0
	v_lshlrev_b32_e32 v2, 4, v1
	v_mov_b32_e32 v3, v0
	v_lshl_or_b32 v132, s78, 3, v140
	v_lshl_add_u64 v[130:131], s[0:1], 0, v[2:3]
	v_and_or_b32 v2, v4, 16, v9
	v_lshrrev_b32_e32 v10, 1, v132
	v_lshlrev_b32_e32 v2, 7, v2
	v_xor_b32_e32 v6, v10, v138
	v_mov_b32_e32 v133, v0
	v_lshl_or_b32 v203, s19, 13, v2
	v_lshlrev_b64 v[2:3], 10, v[132:133]
	v_lshlrev_b32_e32 v6, 4, v6
	v_lshl_add_u64 v[4:5], s[8:9], 0, v[2:3]
	v_and_b32_e32 v6, 0x70, v6
	v_mov_b32_e32 v7, v0
	v_lshl_add_u64 v[140:141], v[4:5], 0, v[6:7]
	v_lshlrev_b32_e32 v5, 1, v1
	v_lshl_add_u64 v[134:135], s[16:17], 0, v[6:7]
	v_bfe_u32 v4, v136, 1, 3
	v_bitop3_b32 v6, v5, v8, 7 bitop3:0x78
	v_lshlrev_b32_e32 v133, 4, v6
	v_bitop3_b32 v6, v5, v4, 1 bitop3:0x36
	v_lshrrev_b32_e32 v9, 1, v9
	v_lshlrev_b32_e32 v205, 4, v6
	v_bitop3_b32 v6, v5, v4, 4 bitop3:0x36
	v_bitop3_b32 v4, v5, v4, 5 bitop3:0x36
	s_lshl_b32 s0, s78, 10
	v_lshlrev_b32_e32 v207, 4, v4
	s_add_i32 s1, 0, 0x10000
	v_xor_b32_e32 v4, v9, v1
	s_add_i32 s33, s0, 0
	s_add_i32 s66, s0, s1
	v_lshlrev_b32_e32 v209, 4, v4
	v_bitop3_b32 v4, v9, v1, 2 bitop3:0x1e
	s_lshl_b32 s0, s18, 14
	s_add_i32 s36, s33, 0x2000
	s_add_i32 s37, s33, 0x4000
	s_add_i32 s38, s33, 0x6000
	s_add_i32 s39, s33, 0x8000
	s_add_i32 s56, s33, 0xa000
	s_add_i32 s57, s33, 0xc000
	s_add_i32 s62, s33, 0xe000
	s_add_i32 s63, s33, 0x16000
	s_add_i32 s64, s33, 0x14000
	s_add_i32 s65, s33, 0x12000
	s_add_i32 s67, s33, 0x1e000
	s_add_i32 s70, s33, 0x1c000
	s_add_i32 s71, s33, 0x1a000
	s_add_i32 s72, s33, 0x18000
	v_lshlrev_b32_e32 v210, 4, v4
	v_bitop3_b32 v4, v9, v1, 4 bitop3:0x1e
	v_bitop3_b32 v1, v9, v1, 6 bitop3:0x1e
	s_add_i32 s1, s1, s0
	v_lshlrev_b32_e32 v212, 4, v1
	s_cmp_eq_u32 s19, 1
	v_readlane_b32 s0, v250, 9
	v_and_b32_e32 v1, 4, v137
	v_readlane_b32 s40, v250, 26
	v_lshlrev_b32_e32 v211, 4, v4
	s_cselect_b64 s[16:17], -1, 0
	v_lshl_add_u32 v214, v136, 2, s1
	s_cmpk_lt_u32 s0, 0x100
	v_lshlrev_b32_e32 v4, 2, v1
	v_mov_b32_e32 v5, v0
	v_readlane_b32 s50, v250, 36
	v_readlane_b32 s51, v250, 37
	v_readlane_b32 s0, v250, 47
	v_lshlrev_b32_e32 v204, 7, v139
	v_readlane_b32 s1, v250, 48
	v_lshl_add_u64 v[142:143], s[50:51], 0, v[4:5]
	v_lshlrev_b32_e32 v4, 1, v1
	v_bitop3_b32 v1, v10, 7, v138 bitop3:0x48
	v_cmp_lt_u32_e64 s[2:3], 31, v136
	v_cmp_gt_u32_e64 s[4:5], 32, v136
	v_lshlrev_b32_e32 v206, 4, v6
	v_add_u32_e32 v208, 0, v203
	v_add_u32_e32 v213, 0, v204
	s_cselect_b64 s[24:25], -1, 0
	v_lshl_or_b32 v139, s18, 5, v139
	v_lshl_add_u64 v[144:145], s[0:1], 0, v[4:5]
	v_lshlrev_b32_e32 v146, 4, v1
	v_mov_b32_e32 v147, v0
	s_lshl_b32 s73, s22, 7
	s_lshl_b32 s74, s82, 7
	v_lshl_add_u64 v[148:149], s[80:81], 0, v[2:3]
	s_sub_i32 s75, 0, s23
	s_mov_b32 s85, 0x8080
	s_mov_b64 s[26:27], 0x80
	s_mov_b64 s[28:29], 0x100
	s_mov_b64 s[30:31], 0x20000
	s_mov_b32 s86, 0x41000000
	v_mov_b32_e32 v215, 0x358637bd
	v_mov_b32_e32 v216, 0x260
	s_mov_b32 s87, 0x3f4ccccd
	v_mov_b32_e32 v217, 0xf149f2ca
	s_mov_b32 s88, s22
	v_readlane_b32 s41, v250, 27
	v_readlane_b32 s42, v250, 28
	v_readlane_b32 s43, v250, 29
	v_readlane_b32 s44, v250, 30
	v_readlane_b32 s45, v250, 31
	v_readlane_b32 s46, v250, 32
	v_readlane_b32 s47, v250, 33
	v_readlane_b32 s48, v250, 34
	v_readlane_b32 s49, v250, 35
	v_readlane_b32 s52, v250, 38
	v_readlane_b32 s53, v250, 39
	v_readlane_b32 s54, v250, 40
	v_readlane_b32 s55, v250, 41
	v_add_u32_e32 v209, v209, v203
	v_add_u32_e32 v210, v210, v203
	v_add_u32_e32 v211, v211, v203
	v_add_u32_e32 v212, v212, v203
	v_add_u32_e32 v133, v133, v204
	v_add_u32_e32 v205, v205, v204
	v_add_u32_e32 v206, v206, v204
	v_add_u32_e32 v207, v207, v204
	s_branch .LBB0_450
